# attention KV loop: next tile K/V global loads issued at the start of each half-step (half-step 1 staged through v[234:253]); ablation showed ~30 us exposed vmcnt wait
# baseline (speedup 1.0000x reference)
; __device__ __forceinline__ int v_st(int k, int c) { const int kk = (k & ~0xC) | ((k & 4) << 1) | ((k & 8) >> 1); return ((kk >> 3) * 4 + (c >> 5)) * 512 + ((kk & 7) * 32 + (c & 31)) * 2; }
; __device__ __forceinline__ int v_rd_base(int lane) { return ((lane & 3) << 3) | (((lane >> 2) & 3) << 6) | (((lane >> 4) & 1) << 5) | (((lane >> 5) & 1) << 8); }
; __device__ __forceinline__ void partialSM(f32x16& p0, f32x16& p1, float& m_reg, float& mn, float& alpha) {
;     float pmax = p0[0]; for (int r = 1; r < 16; ++r) pmax = fmaxf(pmax, p0[r]); for (int r = 0; r < 16; ++r) pmax = fmaxf(pmax, p1[r]);
;     { auto rr = __builtin_amdgcn_permlane32_swap(__float_as_uint(pmax), __float_as_uint(pmax), false, false);
;       pmax = fmaxf(__uint_as_float(rr[0]), __uint_as_float(rr[1])); }
;     constexpr float C2 = 1.4426950408889634f * SCALE;
;     if (__builtin_expect(__all((pmax - m_reg) * SCALE <= THR), 1)) { mn = m_reg; alpha = 1.f; }
;     else { mn = fmaxf(m_reg, pmax); alpha = __builtin_amdgcn_exp2f((m_reg - mn) * C2); m_reg = mn; }
;     const float mnL = -mn * C2;
;     for (int r = 0; r < 16; ++r) p0[r] = fmaf(p0[r], C2, mnL); for (int r = 0; r < 16; ++r) p1[r] = fmaf(p1[r], C2, mnL);
;     for (int r = 0; r < 16; ++r) p0[r] = __builtin_amdgcn_exp2f(p0[r]);
; }
; __device__ __forceinline__ void attn_block(const BlockRef& cur, const BlockRef& nxt, int skv, int W, char* lds, Seam& S) {
;     ...
;     float m_reg = -1e30f, l_reg = 0; f32x16 o[4] = {};
;     const int sr = tid >> 4, sc = (tid & 15) * 8, vst0 = v_st(sr, sc), vst1 = v_st(32 + sr, sc);
;     const int kr_ = tid >> 3, kc_ = (tid & 7) * 8, kws = KSWZ(kr_, kc_ * 2);
;     const int vb0 = (int)(uintptr_t)V_lds + v_rd_base(lane);
;     const bf16* Kh = cur.K; const bf16* Vh = cur.V;
.LBB0_531:
	v_max_f32_e32 v33, 0xf149f2ca, v32
	v_cndmask_b32_e64 v172, v33, v199, s[0:1]
	v_mul_f32_e32 v32, 0xbdd53b94, v172
	v_fmamk_f32 v16, v16, 0x3dd53b94, v32
	v_exp_f32_e32 v153, v16
	v_sub_f32_e32 v16, 0xf149f2ca, v33
	v_mul_f32_e32 v16, 0x3dd53b94, v16
	v_exp_f32_e32 v16, v16
	v_fmamk_f32 v17, v17, 0x3dd53b94, v32
	v_fmamk_f32 v18, v18, 0x3dd53b94, v32
	v_fmamk_f32 v19, v19, 0x3dd53b94, v32
	v_cndmask_b32_e64 v216, v16, 1.0, s[0:1]
	s_and_b32 s0, s67, 0x3fffffc0
	s_lshl_b32 s0, s0, 2
	v_fmamk_f32 v20, v20, 0x3dd53b94, v32
	v_fmamk_f32 v21, v21, 0x3dd53b94, v32
	v_fmamk_f32 v22, v22, 0x3dd53b94, v32
	v_fmamk_f32 v23, v23, 0x3dd53b94, v32
	v_fmamk_f32 v24, v24, 0x3dd53b94, v32
	v_fmamk_f32 v25, v25, 0x3dd53b94, v32
	v_fmamk_f32 v26, v26, 0x3dd53b94, v32
	v_fmamk_f32 v27, v27, 0x3dd53b94, v32
	v_fmamk_f32 v28, v28, 0x3dd53b94, v32
	v_fmamk_f32 v29, v29, 0x3dd53b94, v32
	v_fmamk_f32 v30, v30, 0x3dd53b94, v32
	v_fmamk_f32 v31, v31, 0x3dd53b94, v32
	s_waitcnt vmcnt(3)
	v_pk_fma_f32 v[114:115], v[0:1], s[18:19], v[32:33] op_sel_hi:[1,0,0]
	s_add_i32 s0, s0, 0
	v_lshlrev_b32_e32 v1, 4, v201
	v_exp_f32_e32 v155, v17
	v_exp_f32_e32 v127, v18
	v_exp_f32_e32 v154, v19
	v_exp_f32_e32 v126, v20
	v_exp_f32_e32 v152, v21
	v_exp_f32_e32 v124, v22
	v_exp_f32_e32 v125, v23
	v_exp_f32_e32 v120, v24
	v_exp_f32_e32 v123, v25
	v_exp_f32_e32 v118, v26
	v_exp_f32_e32 v121, v27
	v_exp_f32_e32 v116, v28
	v_exp_f32_e32 v122, v29
	v_exp_f32_e32 v117, v30
	v_exp_f32_e32 v119, v31
	v_pk_fma_f32 v[112:113], v[2:3], s[18:19], v[32:33] op_sel_hi:[1,0,0]
	s_add_i32 s0, s0, 0x14000
	v_lshlrev_b32_e32 v0, 3, v201
	v_and_b32_e32 v1, 0xc0, v1
	v_lshlrev_b32_e32 v2, 1, v201
	v_and_or_b32 v1, v0, 24, v1
	v_and_b32_e32 v2, 32, v2
	v_and_b32_e32 v0, 0x100, v0
	s_cmp_lg_u32 0, -1
	v_or3_b32 v0, v1, v2, v0
	s_cselect_b32 s1, 0, 0
	v_pk_fma_f32 v[110:111], v[14:15], s[18:19], v[32:33] op_sel_hi:[1,0,0]
	v_pk_fma_f32 v[108:109], v[12:13], s[18:19], v[32:33] op_sel_hi:[1,0,0]
	s_waitcnt vmcnt(0)
	v_pk_fma_f32 v[106:107], v[10:11], s[18:19], v[32:33] op_sel_hi:[1,0,0]
	v_pk_fma_f32 v[104:105], v[8:9], s[18:19], v[32:33] op_sel_hi:[1,0,0]
	v_pk_fma_f32 v[102:103], v[6:7], s[18:19], v[32:33] op_sel_hi:[1,0,0]
	v_pk_fma_f32 v[100:101], v[4:5], s[18:19], v[32:33] op_sel_hi:[1,0,0]
	v_add_u32_e32 v206, s1, v0
	s_cmp_lt_i32 s66, 3
	v_add_u32_e32 v223, 0xe000, v212
	v_add_u32_e32 v221, 0xe000, v213
	v_add_u32_e32 v222, 0xe000, v215
	v_add_u32_e32 v220, 0xe000, v214
	v_cmp_gt_u32_e64 s[4:5], 32, v201
	v_lshl_add_u32 v205, v210, 2, s0
	v_lshl_add_u32 v204, v202, 2, s0
	s_waitcnt lgkmcnt(0)
	s_barrier
	s_cbranch_scc1 .LBB0_550
	s_add_i32 s0, s35, 0xffffef45
	v_add_u32_e32 v0, s0, v210
	v_mov_b32_e32 v191, v189
	v_sub_u32_e32 v0, v0, v202
	v_mov_b32_e32 v217, 0
	v_lshl_add_u64 v[194:195], s[54:55], 0, v[188:189]
	v_lshl_add_u64 v[196:197], s[48:49], 0, v[190:191]
	v_lshlrev_b32_e32 v48, 13, v193
	v_mov_b32_e32 v49, 0
	v_lshl_add_u64 v[194:195], v[48:49], 0, v[194:195]
	v_mul_u32_u24_e32 v48, s9, v209
	v_lshl_add_u64 v[196:197], v[48:49], 0, v[196:197]
	s_mov_b32 s54, 2
	v_subrev_u32_e32 v191, s68, v0
	s_add_i32 s55, s68, 0x7f
	v_mov_b32_e32 v48, 0
	v_mov_b32_e32 v49, v217
	v_mov_b32_e32 v50, v217
	v_mov_b32_e32 v51, v217
	v_mov_b32_e32 v52, v217
	v_mov_b32_e32 v53, v217
	v_mov_b32_e32 v54, v217
	v_mov_b32_e32 v55, v217
	v_mov_b32_e32 v56, v217
	v_mov_b32_e32 v57, v217
	v_mov_b32_e32 v58, v217
	v_mov_b32_e32 v59, v217
	v_mov_b32_e32 v60, v217
	v_mov_b32_e32 v61, v217
	v_mov_b32_e32 v62, v217
	v_mov_b32_e32 v63, v217
	v_mov_b32_e32 v32, 0
	v_mov_b32_e32 v33, v217
	v_mov_b32_e32 v34, v217
	v_mov_b32_e32 v35, v217
	v_mov_b32_e32 v36, v217
	v_mov_b32_e32 v37, v217
	v_mov_b32_e32 v38, v217
	v_mov_b32_e32 v39, v217
	v_mov_b32_e32 v40, v217
	v_mov_b32_e32 v41, v217
	v_mov_b32_e32 v42, v217
	v_mov_b32_e32 v43, v217
	v_mov_b32_e32 v44, v217
	v_mov_b32_e32 v45, v217
	v_mov_b32_e32 v46, v217
	v_mov_b32_e32 v47, v217
	v_mov_b32_e32 v16, 0
	v_mov_b32_e32 v17, v217
	v_mov_b32_e32 v18, v217
	v_mov_b32_e32 v19, v217
	v_mov_b32_e32 v20, v217
	v_mov_b32_e32 v21, v217
	v_mov_b32_e32 v22, v217
	v_mov_b32_e32 v23, v217
	v_mov_b32_e32 v24, v217
	v_mov_b32_e32 v25, v217
	v_mov_b32_e32 v26, v217
	v_mov_b32_e32 v27, v217
	v_mov_b32_e32 v28, v217
	v_mov_b32_e32 v29, v217
	v_mov_b32_e32 v30, v217
	v_mov_b32_e32 v31, v217
	v_mov_b32_e32 v0, 0
	v_mov_b32_e32 v1, v217
	v_mov_b32_e32 v2, v217
	v_mov_b32_e32 v3, v217
	v_mov_b32_e32 v4, v217
	v_mov_b32_e32 v5, v217
	v_mov_b32_e32 v6, v217
	v_mov_b32_e32 v7, v217
	v_mov_b32_e32 v8, v217
	v_mov_b32_e32 v9, v217
	v_mov_b32_e32 v10, v217
	v_mov_b32_e32 v11, v217
	v_mov_b32_e32 v12, v217
	v_mov_b32_e32 v13, v217
	v_mov_b32_e32 v14, v217
	v_mov_b32_e32 v15, v217
	s_branch .LBB0_535

; __device__ __forceinline__ void finishSM(f32x16& p0, f32x16& p1, float alpha, float& l_reg, bf16x8& pa0, bf16x8& pa1, bf16x8& pa2, bf16x8& pa3) {
;     for (int r = 0; r < 16; ++r) p1[r] = __builtin_amdgcn_exp2f(p1[r]);
;     float ps = 0; for (int r = 0; r < 16; ++r) ps += p0[r]; for (int r = 0; r < 16; ++r) ps += p1[r];
;     { auto rr = __builtin_amdgcn_permlane32_swap(__float_as_uint(ps), __float_as_uint(ps), false, false);
;       ps = __uint_as_float(rr[0]) + __uint_as_float(rr[1]); }
;     l_reg = l_reg * alpha + ps;
;     ...
;     PK4(p0, 0, pa0); PK4(p0, 8, pa1); PK4(p1, 0, pa2); PK4(p1, 8, pa3);
;     ...
; }
; template <int KB>
; __device__ __forceinline__ void qkt(f32x16& p0, f32x16& p1, const char* K_lds, int r32, int hi, const bf16x8* qr, const char* q_lds) {
;     p0 = f32x16{}; p1 = f32x16{};
;     const char* kb[4];
; #pragma unroll
;     for (int dd = 0; dd < 4; ++dd) kb[dd] = K_lds + KB * SHM_K + KSWZ(r32, (dd * 16 + hi * 8) * 2);
; #pragma unroll
;     for (int d0 = 0; d0 < 12; ++d0) { const char* a = kb[d0 & 3] + (d0 >> 2) * 128;
;         bf16x8 b0 = *reinterpret_cast<const bf16x8*>(a);
;         bf16x8 b1 = *reinterpret_cast<const bf16x8*>(a + 32 * 384);
;         const bf16x8 qf = d0 < NQR ? qr[d0 < NQR ? d0 : 0] : *reinterpret_cast<const bf16x8*>(q_lds + (d0 - NQR) * 1024);
;         p0 = __builtin_amdgcn_mfma_f32_32x32x16_bf16(b0, qf, p0, 0, 0, 0);
;         p1 = __builtin_amdgcn_mfma_f32_32x32x16_bf16(b1, qf, p1, 0, 0, 0); }
; }
.LBB0_535:
	s_add_i32 s100, s55, 1
	s_lshl_b32 s100, s100, 13
	s_mov_b32 s101, 0
	v_lshl_add_u64 v[234:235], s[100:101], 0, v[194:195]
	s_add_i32 s100, s100, 0x40000
	v_lshl_add_u64 v[238:239], s[100:101], 0, v[194:195]
	global_load_dwordx4 v[234:237], v[234:235], off
	global_load_dwordx4 v[238:241], v[238:239], off
	s_add_i32 s100, s55, 1
	s_mul_i32 s100, s100, s9
	v_lshl_add_u64 v[242:243], s[100:101], 0, v[196:197]
	global_load_dwordx4 v[246:249], v[242:243], off offset:128
	global_load_dwordx4 v[250:253], v[242:243], off offset:256
	global_load_dwordx4 v[242:245], v[242:243], off
	ds_read_b128 v[64:67], v212 offset:57344
	ds_read_b128 v[68:71], v223 offset:12288
	v_exp_f32_e32 v114, v114
	v_exp_f32_e32 v115, v115
	v_exp_f32_e32 v112, v112
	s_waitcnt lgkmcnt(1)
	v_mfma_f32_32x32x16_bf16 v[84:99], v[64:67], v[148:151], 0
	ds_read_b128 v[64:67], v213 offset:57344
	ds_read_b128 v[156:159], v221 offset:12288
	v_exp_f32_e32 v113, v113
	v_exp_f32_e32 v164, v108
	v_exp_f32_e32 v165, v109
	v_exp_f32_e32 v166, v110
	v_exp_f32_e32 v111, v111
	s_waitcnt lgkmcnt(2)
	v_mfma_f32_32x32x16_bf16 v[68:83], v[68:71], v[148:151], 0
	s_waitcnt lgkmcnt(1)
	v_mfma_f32_32x32x16_bf16 v[84:99], v[64:67], v[144:147], v[84:99]
	s_waitcnt lgkmcnt(0)
	v_mfma_f32_32x32x16_bf16 v[68:83], v[156:159], v[144:147], v[68:83]
	ds_read_b128 v[64:67], v215 offset:57344
	ds_read_b128 v[156:159], v222 offset:12288
	s_waitcnt lgkmcnt(1)
	v_mfma_f32_32x32x16_bf16 v[84:99], v[64:67], v[140:143], v[84:99]
	s_waitcnt lgkmcnt(0)
	v_mfma_f32_32x32x16_bf16 v[68:83], v[156:159], v[140:143], v[68:83]
	ds_read_b128 v[64:67], v214 offset:57344
	ds_read_b128 v[156:159], v220 offset:12288
	s_waitcnt lgkmcnt(1)
	v_mfma_f32_32x32x16_bf16 v[84:99], v[64:67], v[136:139], v[84:99]
	s_waitcnt lgkmcnt(0)
	v_mfma_f32_32x32x16_bf16 v[68:83], v[156:159], v[136:139], v[68:83]
	ds_read_b128 v[64:67], v212 offset:57472
	ds_read_b128 v[156:159], v223 offset:12416
	s_waitcnt lgkmcnt(1)
	v_mfma_f32_32x32x16_bf16 v[84:99], v[64:67], v[132:135], v[84:99]
	s_waitcnt lgkmcnt(0)
	v_mfma_f32_32x32x16_bf16 v[68:83], v[156:159], v[132:135], v[68:83]
	ds_read_b128 v[64:67], v213 offset:57472
	ds_read_b128 v[156:159], v221 offset:12416
	s_waitcnt lgkmcnt(1)
	v_mfma_f32_32x32x16_bf16 v[84:99], v[64:67], v[128:131], v[84:99]
	s_waitcnt lgkmcnt(0)
	v_mfma_f32_32x32x16_bf16 v[68:83], v[156:159], v[128:131], v[68:83]
	ds_read_b128 v[64:67], v215 offset:57472
	ds_read_b128 v[156:159], v222 offset:12416
	ds_read_b128 v[160:163], v211
	s_waitcnt lgkmcnt(0)
	v_mfma_f32_32x32x16_bf16 v[84:99], v[64:67], v[160:163], v[84:99]
	v_mfma_f32_32x32x16_bf16 v[68:83], v[156:159], v[160:163], v[68:83]
	ds_read_b128 v[64:67], v214 offset:57472
	ds_read_b128 v[156:159], v220 offset:12416
	ds_read_b128 v[160:163], v211 offset:1024
	s_waitcnt lgkmcnt(0)
	v_mfma_f32_32x32x16_bf16 v[84:99], v[64:67], v[160:163], v[84:99]
	v_mfma_f32_32x32x16_bf16 v[68:83], v[156:159], v[160:163], v[68:83]
	ds_read_b128 v[64:67], v212 offset:57600
	ds_read_b128 v[156:159], v223 offset:12544
	ds_read_b128 v[160:163], v211 offset:2048
	s_waitcnt lgkmcnt(0)
	v_mfma_f32_32x32x16_bf16 v[84:99], v[64:67], v[160:163], v[84:99]
	v_mfma_f32_32x32x16_bf16 v[68:83], v[156:159], v[160:163], v[68:83]
	ds_read_b128 v[64:67], v213 offset:57600
	ds_read_b128 v[156:159], v221 offset:12544
	ds_read_b128 v[160:163], v211 offset:3072
	s_waitcnt lgkmcnt(0)
	v_mfma_f32_32x32x16_bf16 v[84:99], v[64:67], v[160:163], v[84:99]
	v_mfma_f32_32x32x16_bf16 v[68:83], v[156:159], v[160:163], v[68:83]
	ds_read_b128 v[64:67], v215 offset:57600
	ds_read_b128 v[156:159], v222 offset:12544
	ds_read_b128 v[160:163], v211 offset:4096
	s_waitcnt lgkmcnt(0)
	v_mfma_f32_32x32x16_bf16 v[84:99], v[64:67], v[160:163], v[84:99]
	v_mfma_f32_32x32x16_bf16 v[68:83], v[156:159], v[160:163], v[68:83]
	ds_read_b128 v[64:67], v214 offset:57600
	ds_read_b128 v[156:159], v220 offset:12544
	ds_read_b128 v[160:163], v211 offset:5120
	s_waitcnt lgkmcnt(0)
	v_mfma_f32_32x32x16_bf16 v[84:99], v[64:67], v[160:163], v[84:99]
	v_add_f32_e32 v64, 0, v153
	v_add_f32_e32 v64, v155, v64
	v_add_f32_e32 v64, v127, v64
	v_add_f32_e32 v64, v154, v64
	v_add_f32_e32 v64, v126, v64
	v_add_f32_e32 v64, v152, v64
	v_add_f32_e32 v64, v124, v64
	v_add_f32_e32 v64, v125, v64
	v_add_f32_e32 v64, v120, v64
	v_add_f32_e32 v64, v123, v64
	v_add_f32_e32 v64, v118, v64
	v_add_f32_e32 v64, v121, v64
	v_add_f32_e32 v64, v116, v64
	v_add_f32_e32 v64, v122, v64
	v_add_f32_e32 v64, v117, v64
	v_add_f32_e32 v64, v119, v64
	v_mfma_f32_32x32x16_bf16 v[68:83], v[156:159], v[160:163], v[68:83]
	v_exp_f32_e32 v156, v100
	v_add_f32_e32 v64, v114, v64
	v_exp_f32_e32 v157, v101
	v_add_f32_e32 v64, v115, v64
	v_exp_f32_e32 v158, v102
	v_add_f32_e32 v64, v112, v64
	v_exp_f32_e32 v159, v103
	v_add_f32_e32 v64, v113, v64
	v_exp_f32_e32 v160, v104
	v_add_f32_e32 v64, v156, v64
	v_exp_f32_e32 v161, v105
	v_add_f32_e32 v64, v157, v64
	v_exp_f32_e32 v162, v106
	v_add_f32_e32 v64, v158, v64
	v_exp_f32_e32 v163, v107
	v_add_f32_e32 v64, v159, v64
	v_add_f32_e32 v64, v160, v64
	v_add_f32_e32 v64, v161, v64
	v_add_f32_e32 v64, v162, v64
	v_add_f32_e32 v64, v163, v64
	v_add_f32_e32 v64, v164, v64
	v_add_f32_e32 v64, v165, v64
	v_add_f32_e32 v64, v166, v64
	v_add_f32_e32 v224, v111, v64
	v_mov_b32_e32 v225, v224
	s_nop 1
	v_permlane32_swap_b32_e32 v224, v225
	v_cvt_pk_bf16_f32 v64, v153, v155
	v_cvt_pk_bf16_f32 v65, v127, v154
	v_cvt_pk_bf16_f32 v66, v126, v152
	v_cvt_pk_bf16_f32 v67, v124, v125
	v_cvt_pk_bf16_f32 v100, v120, v123
	v_cvt_pk_bf16_f32 v101, v118, v121
	v_cvt_pk_bf16_f32 v102, v116, v122
	v_cvt_pk_bf16_f32 v103, v117, v119
	v_cvt_pk_bf16_f32 v104, v114, v115
	v_cvt_pk_bf16_f32 v105, v112, v113
	v_cvt_pk_bf16_f32 v106, v156, v157
	v_cvt_pk_bf16_f32 v107, v158, v159
	v_cvt_pk_bf16_f32 v108, v160, v161
	v_cvt_pk_bf16_f32 v109, v162, v163
	v_cvt_pk_bf16_f32 v110, v164, v165
	v_cvt_pk_bf16_f32 v111, v166, v111
	s_nop 0
	v_permlane32_swap_b32_e32 v64, v66
	v_permlane32_swap_b32_e32 v65, v67
	v_permlane32_swap_b32_e32 v100, v102
	v_permlane32_swap_b32_e32 v101, v103
	v_permlane32_swap_b32_e32 v104, v106
	v_permlane32_swap_b32_e32 v105, v107
	v_permlane32_swap_b32_e32 v108, v110
	v_permlane32_swap_b32_e32 v109, v111
	ds_read_b64_tr_b16 v[112:113], v206 offset:0
	ds_read_b64_tr_b16 v[114:115], v206 offset:0x800
	ds_read_b64_tr_b16 v[116:117], v206 offset:0x1000
	ds_read_b64_tr_b16 v[118:119], v206 offset:0x1800
	ds_read_b64_tr_b16 v[120:121], v206 offset:0x2000
	ds_read_b64_tr_b16 v[122:123], v206 offset:0x2800
	ds_read_b64_tr_b16 v[124:125], v206 offset:0x3000
	ds_read_b64_tr_b16 v[126:127], v206 offset:0x3800
	s_waitcnt lgkmcnt(0)
; __device__ __forceinline__ void mask_tile(f32x16& p0, f32x16& p1, int dq, unsigned W) {
;     const float NEG = -__builtin_inff();
; #pragma unroll
;     for (int r = 0; r < 16; ++r) {
;         const int c = (r & 3) + 8 * (r >> 2);
;         if ((unsigned)(dq - c) >= W) p0[r] = NEG;
;         if ((unsigned)(dq - c - 32) >= W) p1[r] = NEG;
;     }
; }
; template <int VB>
; __device__ __forceinline__ void pv_tile(f32x16* o, int vb0, bf16x8 pa0, bf16x8 pa1, bf16x8 pa2, bf16x8 pa3) {
;     ...
;     PV_D0(0); PV_D0(1); PV_D0(2); PV_D0(3);
	s_nop 0
	v_mfma_f32_32x32x16_bf16 v[48:63], v[64:67], v[112:115], v[48:63]
	ds_read_b64_tr_b16 v[112:113], v206 offset:0x200
	ds_read_b64_tr_b16 v[114:115], v206 offset:0xa00
	v_mfma_f32_32x32x16_bf16 v[48:63], v[100:103], v[116:119], v[48:63]
	ds_read_b64_tr_b16 v[116:117], v206 offset:0x1200
	ds_read_b64_tr_b16 v[118:119], v206 offset:0x1a00
	v_mfma_f32_32x32x16_bf16 v[48:63], v[104:107], v[120:123], v[48:63]
	ds_read_b64_tr_b16 v[120:121], v206 offset:0x2200
	ds_read_b64_tr_b16 v[122:123], v206 offset:0x2a00
	ds_read_b64_tr_b16 v[174:175], v206 offset:0x3200
	ds_read_b64_tr_b16 v[176:177], v206 offset:0x3a00
	s_waitcnt lgkmcnt(0)
	v_mfma_f32_32x32x16_bf16 v[48:63], v[108:111], v[124:127], v[48:63]
	v_mfma_f32_32x32x16_bf16 v[32:47], v[64:67], v[112:115], v[32:47]
	ds_read_b64_tr_b16 v[112:113], v206 offset:0x400
	ds_read_b64_tr_b16 v[114:115], v206 offset:0xc00
	v_mfma_f32_32x32x16_bf16 v[32:47], v[100:103], v[116:119], v[32:47]
	ds_read_b64_tr_b16 v[116:117], v206 offset:0x1400
	ds_read_b64_tr_b16 v[118:119], v206 offset:0x1c00
	v_mfma_f32_32x32x16_bf16 v[32:47], v[104:107], v[120:123], v[32:47]
	ds_read_b64_tr_b16 v[120:121], v206 offset:0x2400
	ds_read_b64_tr_b16 v[122:123], v206 offset:0x2c00
	ds_read_b64_tr_b16 v[124:125], v206 offset:0x3400
	ds_read_b64_tr_b16 v[126:127], v206 offset:0x3c00
	s_waitcnt lgkmcnt(0)
	v_mfma_f32_32x32x16_bf16 v[32:47], v[108:111], v[174:177], v[32:47]
	v_mfma_f32_32x32x16_bf16 v[16:31], v[64:67], v[112:115], v[16:31]
	ds_read_b64_tr_b16 v[112:113], v206 offset:0x600
	ds_read_b64_tr_b16 v[114:115], v206 offset:0xe00
	v_mfma_f32_32x32x16_bf16 v[16:31], v[100:103], v[116:119], v[16:31]
	ds_read_b64_tr_b16 v[116:117], v206 offset:0x1600
	ds_read_b64_tr_b16 v[118:119], v206 offset:0x1e00
	v_mfma_f32_32x32x16_bf16 v[16:31], v[104:107], v[120:123], v[16:31]
	ds_read_b64_tr_b16 v[120:121], v206 offset:0x2600
	ds_read_b64_tr_b16 v[122:123], v206 offset:0x2e00
	ds_read_b64_tr_b16 v[174:175], v206 offset:0x3600
	ds_read_b64_tr_b16 v[176:177], v206 offset:0x3e00
	s_waitcnt lgkmcnt(0)
	v_mfma_f32_32x32x16_bf16 v[16:31], v[108:111], v[124:127], v[16:31]
	v_mfma_f32_32x32x16_bf16 v[0:15], v[64:67], v[112:115], v[0:15]
	s_sub_i32 s48, s55, 63
	s_cmp_le_i32 s55, s35
	s_cselect_b64 s[0:1], -1, 0
	s_cmp_gt_i32 s48, s47
	s_cselect_b64 s[48:49], -1, 0
	s_and_b64 s[0:1], s[0:1], s[48:49]
	s_and_b64 vcc, exec, s[0:1]
	v_mfma_f32_32x32x16_bf16 v[0:15], v[100:103], v[116:119], v[0:15]
	v_mfma_f32_32x32x16_bf16 v[0:15], v[104:107], v[120:123], v[0:15]
	v_mfma_f32_32x32x16_bf16 v[0:15], v[108:111], v[174:177], v[0:15]
	s_cbranch_vccnz .LBB0_537
	v_add_u32_e32 v64, 0x107b, v191
	v_cmp_gt_u32_e32 vcc, s33, v64
	v_add_u32_e32 v64, 0x5b, v191
	s_nop 0
	v_cndmask_b32_e32 v84, v198, v84, vcc
	v_cmp_lt_u32_e32 vcc, s56, v64
	v_add_u32_e32 v64, 0x7a, v191
	s_nop 0
	v_cndmask_b32_e32 v68, v198, v68, vcc
	v_cmp_lt_u32_e32 vcc, s56, v64
	v_add_u32_e32 v64, 0x5a, v191
	s_nop 0
	v_cndmask_b32_e32 v85, v198, v85, vcc
	v_cmp_lt_u32_e32 vcc, s56, v64
	v_add_u32_e32 v64, 0x79, v191
	s_nop 0
	v_cndmask_b32_e32 v69, v198, v69, vcc
	v_cmp_lt_u32_e32 vcc, s56, v64
	v_add_u32_e32 v64, 0x59, v191
	s_nop 0
	v_cndmask_b32_e32 v86, v198, v86, vcc
	v_cmp_lt_u32_e32 vcc, s56, v64
	v_add_u32_e32 v64, 0x78, v191
	s_nop 0
	v_cndmask_b32_e32 v70, v198, v70, vcc
	v_cmp_lt_u32_e32 vcc, s56, v64
	v_add_u32_e32 v64, 0x58, v191
	s_nop 0
	v_cndmask_b32_e32 v87, v198, v87, vcc
	v_cmp_lt_u32_e32 vcc, s56, v64
	v_add_u32_e32 v64, 0x73, v191
	s_nop 0
	v_cndmask_b32_e32 v71, v198, v71, vcc
	v_cmp_lt_u32_e32 vcc, s56, v64
	v_add_u32_e32 v64, 0x53, v191
	s_nop 0
	v_cndmask_b32_e32 v88, v198, v88, vcc
	v_cmp_lt_u32_e32 vcc, s56, v64
	v_add_u32_e32 v64, 0x72, v191
	s_nop 0
	v_cndmask_b32_e32 v72, v198, v72, vcc
	v_cmp_lt_u32_e32 vcc, s56, v64
	v_add_u32_e32 v64, 0x52, v191
	s_nop 0
	v_cndmask_b32_e32 v89, v198, v89, vcc
	v_cmp_lt_u32_e32 vcc, s56, v64
	v_add_u32_e32 v64, 0x71, v191
	s_nop 0
	v_cndmask_b32_e32 v73, v198, v73, vcc
	v_cmp_lt_u32_e32 vcc, s56, v64
	v_add_u32_e32 v64, 0x51, v191
	s_nop 0
	v_cndmask_b32_e32 v90, v198, v90, vcc
	v_cmp_lt_u32_e32 vcc, s56, v64
	v_add_u32_e32 v64, 0x70, v191
	s_nop 0
	v_cndmask_b32_e32 v74, v198, v74, vcc
	v_cmp_lt_u32_e32 vcc, s56, v64
	v_add_u32_e32 v64, 0x50, v191
	s_nop 0
	v_cndmask_b32_e32 v91, v198, v91, vcc
	v_cmp_lt_u32_e32 vcc, s56, v64
	v_add_u32_e32 v64, 0x6b, v191
	s_nop 0
	v_cndmask_b32_e32 v75, v198, v75, vcc
	v_cmp_lt_u32_e32 vcc, s56, v64
	v_add_u32_e32 v64, 0x4b, v191
	s_nop 0
	v_cndmask_b32_e32 v92, v198, v92, vcc
	v_cmp_lt_u32_e32 vcc, s56, v64
	v_add_u32_e32 v64, 0x6a, v191
	s_nop 0
	v_cndmask_b32_e32 v76, v198, v76, vcc
	v_cmp_lt_u32_e32 vcc, s56, v64
	v_add_u32_e32 v64, 0x4a, v191
	s_nop 0
	v_cndmask_b32_e32 v93, v198, v93, vcc
	v_cmp_lt_u32_e32 vcc, s56, v64
	v_add_u32_e32 v64, 0x69, v191
	s_nop 0
	v_cndmask_b32_e32 v77, v198, v77, vcc
	v_cmp_lt_u32_e32 vcc, s56, v64
	v_add_u32_e32 v64, 0x49, v191
	s_nop 0
	v_cndmask_b32_e32 v94, v198, v94, vcc
	v_cmp_lt_u32_e32 vcc, s56, v64
	v_add_u32_e32 v64, 0x68, v191
	s_nop 0
	v_cndmask_b32_e32 v78, v198, v78, vcc
	v_cmp_lt_u32_e32 vcc, s56, v64
	v_add_u32_e32 v64, 0x48, v191
	s_nop 0
	v_cndmask_b32_e32 v95, v198, v95, vcc
	v_cmp_lt_u32_e32 vcc, s56, v64
	v_add_u32_e32 v64, 0x63, v191
	s_nop 0
	v_cndmask_b32_e32 v79, v198, v79, vcc
	v_cmp_lt_u32_e32 vcc, s56, v64
	v_add_u32_e32 v64, 0x43, v191
	s_nop 0
	v_cndmask_b32_e32 v96, v198, v96, vcc
	v_cmp_lt_u32_e32 vcc, s56, v64
	v_add_u32_e32 v64, 0x62, v191
	s_nop 0
	v_cndmask_b32_e32 v80, v198, v80, vcc
	v_cmp_lt_u32_e32 vcc, s56, v64
	v_add_u32_e32 v64, 0x42, v191
	s_nop 0
	v_cndmask_b32_e32 v97, v198, v97, vcc
	v_cmp_lt_u32_e32 vcc, s56, v64
	v_add_u32_e32 v64, 0x61, v191
	s_nop 0
	v_cndmask_b32_e32 v81, v198, v81, vcc
	v_cmp_lt_u32_e32 vcc, s56, v64
	v_add_u32_e32 v64, 0x41, v191
	s_nop 0
	v_cndmask_b32_e32 v98, v198, v98, vcc
	v_cmp_lt_u32_e32 vcc, s56, v64
	v_add_u32_e32 v64, 0x60, v191
	s_nop 0
	v_cndmask_b32_e32 v82, v198, v82, vcc
	v_cmp_lt_u32_e32 vcc, s56, v64
	v_add_u32_e32 v64, 64, v191
	s_nop 0
	v_cndmask_b32_e32 v99, v198, v99, vcc
	v_cmp_lt_u32_e32 vcc, s56, v64
	s_nop 1
	v_cndmask_b32_e32 v83, v198, v83, vcc
; #define SBAR() __builtin_amdgcn_sched_barrier(0)
; #define VMW() asm volatile("s_waitcnt vmcnt(0)" ::: "memory")
; #define SLOAD_H(Kp, Vp, k0) do { S.st_v0 = load8(VROW(Vp, k0, sr)); S.st_v1 = load8(VROW(Vp, k0, 32 + sr));              \
;                          S.st_k0 = load8(KROW(Kp, k0)); S.st_k1 = load8(KROW(Kp, k0) + 64); S.st_k2 = load8(KROW(Kp, k0) + 128); } while (0)
; #define SWRITE_HV(bf) do { *(bf16x8*)(V_lds + (bf) * SHM_V + vst0) = S.st_v0; *(bf16x8*)(V_lds + (bf) * SHM_V + vst1) = S.st_v1; } while (0)
; #define SWRITE_H(bf) do { SWRITE_HV(bf); SWRITE_HK(bf); } while (0)
; #define MASKT(P0_, P1_, t) do { const int kb_ = KBASE(t); if (kb_ + KVBLK - 1 > qlo || kb_ <= qlo + QBLK - 1 - W) mask_tile(P0_, P1_, qm - kb_, (unsigned)W); } while (0)
; __device__ __forceinline__ void partialSM(f32x16& p0, f32x16& p1, float& m_reg, float& mn, float& alpha) {
;     float pmax = p0[0]; for (int r = 1; r < 16; ++r) pmax = fmaxf(pmax, p0[r]); for (int r = 0; r < 16; ++r) pmax = fmaxf(pmax, p1[r]);
;     { auto rr = __builtin_amdgcn_permlane32_swap(__float_as_uint(pmax), __float_as_uint(pmax), false, false);
;       pmax = fmaxf(__uint_as_float(rr[0]), __uint_as_float(rr[1])); }
;     constexpr float C2 = 1.4426950408889634f * SCALE;
;     if (__builtin_expect(__all((pmax - m_reg) * SCALE <= THR), 1)) { mn = m_reg; alpha = 1.f; }
;     else { mn = fmaxf(m_reg, pmax); alpha = __builtin_amdgcn_exp2f((m_reg - mn) * C2); m_reg = mn; }
;     const float mnL = -mn * C2;
;     for (int r = 0; r < 16; ++r) p0[r] = fmaf(p0[r], C2, mnL); for (int r = 0; r < 16; ++r) p1[r] = fmaf(p1[r], C2, mnL);
;     for (int r = 0; r < 16; ++r) p0[r] = __builtin_amdgcn_exp2f(p0[r]);
; }
; __device__ __forceinline__ void attn_block(const BlockRef& cur, const BlockRef& nxt, int skv, int W, char* lds, Seam& S) {
;     ...
;     constexpr int NQL = 12;
;     ...
;     f32x16 pA0, pA1, pB0, pB1; float mnA, mnB, alA, alB; bf16x8 pa0, pa1, pa2, pa3;
;     char* q_lds = lds + LDS_Q + (wid * NQL_ * 64 + lane) * 16;
; #pragma unroll
;     for (int d0 = 0; d0 < NQL_; ++d0) *(bf16x8*)(q_lds + d0 * 1024) = S.qt[d0];
;     SWRITE_HV(0); SBAR();
;     if (NT > 1) { SLOAD_H(Kh, Vh, KBASE(1)); }
;     SBAR(); qkt<0>(pA0, pA1, K_lds, r32, hi, S.qr, q_lds);
;     MASKT(pA0, pA1, 0); partialSM(pA0, pA1, m_reg, mnA, alA);
;     if (NT > 1) { VMW(); SWRITE_H(1); }
;     __syncthreads();
.LBB0_537:
	v_max_f32_e32 v64, v85, v85
	v_max_f32_e32 v65, v84, v84
	v_max_f32_e32 v64, v65, v64
	v_max3_f32 v64, v64, v86, v87
	v_max3_f32 v64, v64, v88, v89
	v_max3_f32 v64, v64, v90, v91
	v_max3_f32 v64, v64, v92, v93
	v_max3_f32 v64, v64, v94, v95
	v_max3_f32 v64, v64, v96, v97
	v_max3_f32 v64, v64, v98, v99
	v_max3_f32 v64, v64, v68, v69
	v_max3_f32 v64, v64, v70, v71
	v_max3_f32 v64, v64, v72, v73
	v_max3_f32 v64, v64, v74, v75
	v_max3_f32 v64, v64, v76, v77
	v_max3_f32 v64, v64, v78, v79
	v_max3_f32 v64, v64, v80, v81
	v_max3_f32 v64, v64, v82, v83
	v_mov_b32_e32 v65, v64
	s_nop 1
	v_permlane32_swap_b32_e32 v64, v65
	v_max_f32_e32 v65, v65, v65
	v_max_f32_e32 v64, v64, v64
	v_max_f32_e32 v64, v64, v65
	v_max_f32_e32 v66, v172, v172
	v_sub_f32_e32 v65, v64, v172
	v_max_f32_e32 v64, v66, v64
	v_sub_f32_e32 v66, v172, v64
	v_mul_f32_e32 v66, 0x3dd53b94, v66
	v_mul_f32_e32 v65, 0x3d93cd3a, v65
	v_exp_f32_e32 v66, v66
	v_cmp_ge_f32_e32 vcc, s57, v65
	s_cmp_eq_u64 vcc, exec
	s_cselect_b64 s[0:1], -1, 0
	s_waitcnt vmcnt(0)
	v_cndmask_b32_e64 v227, v66, 1.0, s[0:1]
	v_cmp_gt_f32_e32 vcc, 1.0, v227
	s_waitcnt vmcnt(2)
	ds_write_b128 v203, v[242:245] offset:32768
	s_waitcnt vmcnt(1)
	ds_write_b128 v203, v[246:249] offset:32896
	s_waitcnt vmcnt(0)
	ds_write_b128 v203, v[250:253] offset:33024
	s_cbranch_vccz .LBB0_541
	s_and_saveexec_b64 s[48:49], s[4:5]
	ds_write_b32 v205, v227 offset:128
	s_or_b64 exec, exec, s[48:49]
	s_waitcnt lgkmcnt(0)
	ds_read_b128 v[100:103], v204 offset:224
	ds_read_b128 v[104:107], v204 offset:192
	ds_read_b128 v[108:111], v204 offset:160
	ds_read_b128 v[112:115], v204 offset:128
	s_waitcnt lgkmcnt(3)
	v_pk_mul_f32 v[62:63], v[62:63], v[102:103]
	s_waitcnt lgkmcnt(2)
	v_pk_mul_f32 v[58:59], v[58:59], v[106:107]
	s_waitcnt lgkmcnt(1)
	v_pk_mul_f32 v[54:55], v[54:55], v[110:111]
	s_waitcnt lgkmcnt(0)
	v_pk_mul_f32 v[50:51], v[50:51], v[114:115]
	v_pk_mul_f32 v[60:61], v[60:61], v[100:101]
	v_pk_mul_f32 v[56:57], v[56:57], v[104:105]
	v_pk_mul_f32 v[52:53], v[52:53], v[108:109]
	v_pk_mul_f32 v[48:49], v[48:49], v[112:113]
	v_pk_mul_f32 v[46:47], v[46:47], v[102:103]
	v_pk_mul_f32 v[42:43], v[42:43], v[106:107]
	v_pk_mul_f32 v[38:39], v[38:39], v[110:111]
	v_pk_mul_f32 v[34:35], v[34:35], v[114:115]
	v_pk_mul_f32 v[44:45], v[44:45], v[100:101]
	v_pk_mul_f32 v[40:41], v[40:41], v[104:105]
	v_pk_mul_f32 v[36:37], v[36:37], v[108:109]
	v_pk_mul_f32 v[32:33], v[32:33], v[112:113]
	v_pk_mul_f32 v[30:31], v[30:31], v[102:103]
	v_pk_mul_f32 v[26:27], v[26:27], v[106:107]
	v_pk_mul_f32 v[22:23], v[22:23], v[110:111]
	v_pk_mul_f32 v[18:19], v[18:19], v[114:115]
	v_pk_mul_f32 v[28:29], v[28:29], v[100:101]
	v_pk_mul_f32 v[24:25], v[24:25], v[104:105]
	v_pk_mul_f32 v[20:21], v[20:21], v[108:109]
	v_pk_mul_f32 v[16:17], v[16:17], v[112:113]
	v_pk_mul_f32 v[14:15], v[14:15], v[102:103]
	v_pk_mul_f32 v[10:11], v[10:11], v[106:107]
	v_pk_mul_f32 v[6:7], v[6:7], v[110:111]
	v_pk_mul_f32 v[2:3], v[2:3], v[114:115]
	v_pk_mul_f32 v[12:13], v[12:13], v[100:101]
	v_pk_mul_f32 v[8:9], v[8:9], v[104:105]
	v_pk_mul_f32 v[4:5], v[4:5], v[108:109]
	v_pk_mul_f32 v[0:1], v[0:1], v[112:113]
.LBB0_541:
	v_cndmask_b32_e64 v228, v64, v172, s[0:1]
	v_mul_f32_e32 v172, 0xbdd53b94, v228
	v_fmamk_f32 v64, v84, 0x3dd53b94, v172
	v_fmamk_f32 v65, v85, 0x3dd53b94, v172
	v_fmamk_f32 v66, v86, 0x3dd53b94, v172
	v_fmamk_f32 v67, v87, 0x3dd53b94, v172
	v_fmamk_f32 v100, v88, 0x3dd53b94, v172
	v_fmamk_f32 v101, v89, 0x3dd53b94, v172
	v_fmamk_f32 v102, v90, 0x3dd53b94, v172
	v_fmamk_f32 v103, v91, 0x3dd53b94, v172
	v_fmamk_f32 v104, v92, 0x3dd53b94, v172
	v_fmamk_f32 v105, v93, 0x3dd53b94, v172
	v_fmamk_f32 v106, v94, 0x3dd53b94, v172
	v_fmamk_f32 v107, v95, 0x3dd53b94, v172
	v_fmamk_f32 v96, v96, 0x3dd53b94, v172
	v_fmamk_f32 v97, v97, 0x3dd53b94, v172
	v_fmamk_f32 v98, v98, 0x3dd53b94, v172
	v_fmamk_f32 v99, v99, 0x3dd53b94, v172
	v_fmamk_f32 v84, v68, 0x3dd53b94, v172
	v_fmamk_f32 v93, v69, 0x3dd53b94, v172
	v_fmamk_f32 v94, v70, 0x3dd53b94, v172
	v_fmamk_f32 v95, v71, 0x3dd53b94, v172
	v_fmamk_f32 v173, v72, 0x3dd53b94, v172
	v_fmamk_f32 v85, v73, 0x3dd53b94, v172
	v_fmamk_f32 v86, v74, 0x3dd53b94, v172
	v_fmamk_f32 v87, v75, 0x3dd53b94, v172
	v_fmamk_f32 v88, v76, 0x3dd53b94, v172
	v_fmamk_f32 v89, v77, 0x3dd53b94, v172
	v_fmamk_f32 v90, v78, 0x3dd53b94, v172
	v_fmamk_f32 v91, v79, 0x3dd53b94, v172
	v_exp_f32_e32 v64, v64
	v_exp_f32_e32 v65, v65
	v_exp_f32_e32 v66, v66
	v_exp_f32_e32 v67, v67
	v_exp_f32_e32 v68, v100
	v_exp_f32_e32 v69, v101
	v_exp_f32_e32 v70, v102
	v_exp_f32_e32 v71, v103
	v_exp_f32_e32 v72, v104
	v_exp_f32_e32 v73, v105
	v_exp_f32_e32 v74, v106
	v_exp_f32_e32 v75, v107
	v_exp_f32_e32 v76, v96
	v_exp_f32_e32 v77, v97
	v_exp_f32_e32 v78, v98
	v_exp_f32_e32 v79, v99
	v_fmamk_f32 v92, v80, 0x3dd53b94, v172
	v_fmamk_f32 v174, v81, 0x3dd53b94, v172
	v_fmamk_f32 v175, v82, 0x3dd53b94, v172
	v_fmac_f32_e32 v172, 0x3dd53b94, v83
	s_waitcnt lgkmcnt(0)
	s_barrier
	ds_write_b128 v218, v[234:237]
	ds_write_b128 v219, v[238:241]
	s_add_i32 s0, s54, 1
	s_cmp_lt_i32 s0, s66
	s_cselect_b64 s[48:49], -1, 0
	s_cmp_ge_i32 s0, s66
	s_cbranch_scc1 .Latt_early2_skip
	s_add_i32 s100, s55, 0x41
	s_lshl_b32 s100, s100, 13
	s_mov_b32 s101, 0
	v_lshl_add_u64 v[152:153], s[100:101], 0, v[194:195]
	s_add_i32 s100, s100, 0x40000
	v_lshl_add_u64 v[156:157], s[100:101], 0, v[194:195]
	s_add_i32 s100, s55, 0x41
	s_mul_i32 s100, s100, s9
	v_lshl_add_u64 v[168:169], s[100:101], 0, v[196:197]
	global_load_dwordx4 v[152:155], v[152:153], off
	global_load_dwordx4 v[156:159], v[156:157], off
	global_load_dwordx4 v[160:163], v[168:169], off
	global_load_dwordx4 v[164:167], v[168:169], off offset:128
	global_load_dwordx4 v[168:171], v[168:169], off offset:256
; __device__ __forceinline__ void finishSM(f32x16& p0, f32x16& p1, float alpha, float& l_reg, bf16x8& pa0, bf16x8& pa1, bf16x8& pa2, bf16x8& pa3) {
;     for (int r = 0; r < 16; ++r) p1[r] = __builtin_amdgcn_exp2f(p1[r]);
;     float ps = 0; for (int r = 0; r < 16; ++r) ps += p0[r]; for (int r = 0; r < 16; ++r) ps += p1[r];
;     { auto rr = __builtin_amdgcn_permlane32_swap(__float_as_uint(ps), __float_as_uint(ps), false, false);
;       ps = __uint_as_float(rr[0]) + __uint_as_float(rr[1]); }
;     l_reg = l_reg * alpha + ps;
;     ...
;     PK4(p0, 0, pa0); PK4(p0, 8, pa1); PK4(p1, 0, pa2); PK4(p1, 8, pa3);
;     ...
; }
; template <int KB>
; __device__ __forceinline__ void qkt(f32x16& p0, f32x16& p1, const char* K_lds, int r32, int hi, const bf16x8* qr, const char* q_lds) {
;     p0 = f32x16{}; p1 = f32x16{};
;     const char* kb[4];
; #pragma unroll
;     for (int dd = 0; dd < 4; ++dd) kb[dd] = K_lds + KB * SHM_K + KSWZ(r32, (dd * 16 + hi * 8) * 2);
; #pragma unroll
;     for (int d0 = 0; d0 < 12; ++d0) { const char* a = kb[d0 & 3] + (d0 >> 2) * 128;
;         bf16x8 b0 = *reinterpret_cast<const bf16x8*>(a);
;         bf16x8 b1 = *reinterpret_cast<const bf16x8*>(a + 32 * 384);
;         const bf16x8 qf = d0 < NQR ? qr[d0 < NQR ? d0 : 0] : *reinterpret_cast<const bf16x8*>(q_lds + (d0 - NQR) * 1024);
;         p0 = __builtin_amdgcn_mfma_f32_32x32x16_bf16(b0, qf, p0, 0, 0, 0);
;         p1 = __builtin_amdgcn_mfma_f32_32x32x16_bf16(b1, qf, p1, 0, 0, 0); }
; }
.Latt_early2_skip:
	ds_read_b128 v[80:83], v212 offset:32768
	ds_read_b128 v[96:99], v212 offset:45056
	v_exp_f32_e32 v85, v85
	v_exp_f32_e32 v86, v86
	v_exp_f32_e32 v87, v87
	s_waitcnt lgkmcnt(1)
	v_mfma_f32_32x32x16_bf16 v[112:127], v[80:83], v[148:151], 0
	ds_read_b128 v[80:83], v213 offset:32768
	ds_read_b128 v[176:179], v213 offset:45056
	v_exp_f32_e32 v88, v88
	v_exp_f32_e32 v89, v89
	v_exp_f32_e32 v90, v90
	v_exp_f32_e32 v91, v91
	v_exp_f32_e32 v92, v92
	s_waitcnt lgkmcnt(2)
	v_mfma_f32_32x32x16_bf16 v[96:111], v[96:99], v[148:151], 0
	s_waitcnt lgkmcnt(1)
	v_mfma_f32_32x32x16_bf16 v[112:127], v[80:83], v[144:147], v[112:127]
	s_waitcnt lgkmcnt(0)
	v_mfma_f32_32x32x16_bf16 v[96:111], v[176:179], v[144:147], v[96:111]
	ds_read_b128 v[80:83], v215 offset:32768
	ds_read_b128 v[176:179], v215 offset:45056
	s_waitcnt lgkmcnt(1)
	v_mfma_f32_32x32x16_bf16 v[112:127], v[80:83], v[140:143], v[112:127]
	s_waitcnt lgkmcnt(0)
	v_mfma_f32_32x32x16_bf16 v[96:111], v[176:179], v[140:143], v[96:111]
	ds_read_b128 v[80:83], v214 offset:32768
	ds_read_b128 v[176:179], v214 offset:45056
	s_waitcnt lgkmcnt(1)
	v_mfma_f32_32x32x16_bf16 v[112:127], v[80:83], v[136:139], v[112:127]
	s_waitcnt lgkmcnt(0)
	v_mfma_f32_32x32x16_bf16 v[96:111], v[176:179], v[136:139], v[96:111]
	ds_read_b128 v[80:83], v212 offset:32896
	ds_read_b128 v[176:179], v212 offset:45184
	s_waitcnt lgkmcnt(1)
	v_mfma_f32_32x32x16_bf16 v[112:127], v[80:83], v[132:135], v[112:127]
	s_waitcnt lgkmcnt(0)
	v_mfma_f32_32x32x16_bf16 v[96:111], v[176:179], v[132:135], v[96:111]
	ds_read_b128 v[80:83], v213 offset:32896
	ds_read_b128 v[176:179], v213 offset:45184
	s_waitcnt lgkmcnt(1)
	v_mfma_f32_32x32x16_bf16 v[112:127], v[80:83], v[128:131], v[112:127]
	s_waitcnt lgkmcnt(0)
	v_mfma_f32_32x32x16_bf16 v[96:111], v[176:179], v[128:131], v[96:111]
	ds_read_b128 v[80:83], v215 offset:32896
	ds_read_b128 v[176:179], v215 offset:45184
	ds_read_b128 v[180:183], v211
	s_waitcnt lgkmcnt(0)
	v_mfma_f32_32x32x16_bf16 v[112:127], v[80:83], v[180:183], v[112:127]
	v_mfma_f32_32x32x16_bf16 v[96:111], v[176:179], v[180:183], v[96:111]
	ds_read_b128 v[80:83], v214 offset:32896
	ds_read_b128 v[176:179], v214 offset:45184
	ds_read_b128 v[180:183], v211 offset:1024
	s_waitcnt lgkmcnt(0)
	v_mfma_f32_32x32x16_bf16 v[112:127], v[80:83], v[180:183], v[112:127]
	v_mfma_f32_32x32x16_bf16 v[96:111], v[176:179], v[180:183], v[96:111]
	ds_read_b128 v[80:83], v212 offset:33024
	ds_read_b128 v[176:179], v212 offset:45312
	ds_read_b128 v[180:183], v211 offset:2048
	s_waitcnt lgkmcnt(0)
	v_mfma_f32_32x32x16_bf16 v[112:127], v[80:83], v[180:183], v[112:127]
	v_mfma_f32_32x32x16_bf16 v[96:111], v[176:179], v[180:183], v[96:111]
	ds_read_b128 v[80:83], v213 offset:33024
	ds_read_b128 v[176:179], v213 offset:45312
	ds_read_b128 v[180:183], v211 offset:3072
	s_waitcnt lgkmcnt(0)
	v_mfma_f32_32x32x16_bf16 v[112:127], v[80:83], v[180:183], v[112:127]
	v_mfma_f32_32x32x16_bf16 v[96:111], v[176:179], v[180:183], v[96:111]
	ds_read_b128 v[80:83], v215 offset:33024
	ds_read_b128 v[176:179], v215 offset:45312
	ds_read_b128 v[180:183], v211 offset:4096
	s_waitcnt lgkmcnt(0)
	v_mfma_f32_32x32x16_bf16 v[112:127], v[80:83], v[180:183], v[112:127]
	v_mfma_f32_32x32x16_bf16 v[96:111], v[176:179], v[180:183], v[96:111]
	ds_read_b128 v[80:83], v214 offset:33024
	ds_read_b128 v[176:179], v214 offset:45312
	ds_read_b128 v[180:183], v211 offset:5120
	s_waitcnt lgkmcnt(0)
	v_mfma_f32_32x32x16_bf16 v[112:127], v[80:83], v[180:183], v[112:127]
	v_exp_f32_e32 v83, v95
	v_exp_f32_e32 v95, v172
	v_add_f32_e32 v172, 0, v64
	v_add_f32_e32 v172, v65, v172
	v_add_f32_e32 v172, v66, v172
	v_add_f32_e32 v172, v67, v172
	v_add_f32_e32 v172, v68, v172
	v_add_f32_e32 v172, v69, v172
	v_add_f32_e32 v172, v70, v172
	v_add_f32_e32 v172, v71, v172
	v_add_f32_e32 v172, v72, v172
	v_add_f32_e32 v172, v73, v172
	v_add_f32_e32 v172, v74, v172
	v_add_f32_e32 v172, v75, v172
	v_exp_f32_e32 v80, v84
	v_add_f32_e32 v172, v76, v172
	v_exp_f32_e32 v81, v93
	v_add_f32_e32 v172, v77, v172
	v_exp_f32_e32 v82, v94
	v_add_f32_e32 v172, v78, v172
	v_add_f32_e32 v172, v79, v172
	v_exp_f32_e32 v84, v173
	v_add_f32_e32 v172, v80, v172
	v_add_f32_e32 v172, v81, v172
	v_add_f32_e32 v172, v82, v172
	v_add_f32_e32 v172, v83, v172
	v_add_f32_e32 v172, v84, v172
	v_add_f32_e32 v172, v85, v172
	v_add_f32_e32 v172, v86, v172
	v_add_f32_e32 v172, v87, v172
	v_add_f32_e32 v172, v88, v172
	v_exp_f32_e32 v93, v174
	v_add_f32_e32 v172, v89, v172
	v_mfma_f32_32x32x16_bf16 v[96:111], v[176:179], v[180:183], v[96:111]
	v_exp_f32_e32 v94, v175
	v_add_f32_e32 v172, v90, v172
	v_add_f32_e32 v172, v91, v172
	v_add_f32_e32 v172, v92, v172
	v_add_f32_e32 v172, v93, v172
	v_add_f32_e32 v172, v94, v172
	v_add_f32_e32 v231, v95, v172
	v_mov_b32_e32 v232, v231
	v_cvt_pk_bf16_f32 v172, v64, v65
	v_cvt_pk_bf16_f32 v173, v66, v67
	v_cvt_pk_bf16_f32 v174, v68, v69
	v_cvt_pk_bf16_f32 v175, v70, v71
	v_cvt_pk_bf16_f32 v176, v72, v73
	v_cvt_pk_bf16_f32 v177, v74, v75
	v_cvt_pk_bf16_f32 v178, v76, v77
	v_cvt_pk_bf16_f32 v179, v78, v79
	v_cvt_pk_bf16_f32 v180, v80, v81
	v_cvt_pk_bf16_f32 v181, v82, v83
	v_cvt_pk_bf16_f32 v182, v84, v85
	v_cvt_pk_bf16_f32 v183, v86, v87
	v_cvt_pk_bf16_f32 v184, v88, v89
	v_cvt_pk_bf16_f32 v185, v90, v91
	v_cvt_pk_bf16_f32 v186, v92, v93
	v_cvt_pk_bf16_f32 v187, v94, v95
	s_nop 1
	v_permlane32_swap_b32_e32 v231, v232
	v_permlane32_swap_b32_e32 v172, v174
	v_permlane32_swap_b32_e32 v173, v175
	v_permlane32_swap_b32_e32 v176, v178
	v_permlane32_swap_b32_e32 v177, v179
	v_permlane32_swap_b32_e32 v180, v182
	v_permlane32_swap_b32_e32 v181, v183
	v_permlane32_swap_b32_e32 v184, v186
	v_permlane32_swap_b32_e32 v185, v187
